# MoBA k block-mean reduction rewritten: all 131072 threads, 32 loads in flight per lane, halves combined with permlane32_swap (old loop kept for other grids)
# speedup vs baseline: 1.0103x; 1.0103x over previous
.LBB0_637:
	s_cmp_lg_u32 s74, 0x20000
	s_cbranch_scc1 .Lmy_km_old
	v_readlane_b32 s92, v235, 41
	v_readlane_b32 s93, v235, 42
	v_readlane_b32 s94, v235, 40
	v_lshrrev_b32_e32 v2, 11, v134
	v_and_b32_e32 v3, 0x7ff, v134
	v_lshrrev_b32_e32 v4, 6, v3
	v_and_b32_e32 v5, 31, v3
	v_lshl_or_b32 v4, v4, 5, v5
	v_bfe_u32 v5, v3, 5, 1
	v_lshlrev_b32_e32 v6, 19, v2
	v_lshl_or_b32 v6, v5, 18, v6
	v_lshl_or_b32 v6, v4, 1, v6
	s_add_u32 s10, s8, 0x1b000000
	s_addc_u32 s11, s9, 0
	v_mov_b32_e32 v7, 0
	s_mov_b32 s12, 0
.Lmy_km_loop:
	global_load_ushort v16, v6, s[10:11]
	global_load_ushort v17, v6, s[10:11] offset:2048
	s_add_u32 s10, s10, 0x1000
	s_addc_u32 s11, s11, 0
	global_load_ushort v18, v6, s[10:11]
	global_load_ushort v19, v6, s[10:11] offset:2048
	s_add_u32 s10, s10, 0x1000
	s_addc_u32 s11, s11, 0
	global_load_ushort v20, v6, s[10:11]
	global_load_ushort v21, v6, s[10:11] offset:2048
	s_add_u32 s10, s10, 0x1000
	s_addc_u32 s11, s11, 0
	global_load_ushort v22, v6, s[10:11]
	global_load_ushort v23, v6, s[10:11] offset:2048
	s_add_u32 s10, s10, 0x1000
	s_addc_u32 s11, s11, 0
	global_load_ushort v24, v6, s[10:11]
	global_load_ushort v25, v6, s[10:11] offset:2048
	s_add_u32 s10, s10, 0x1000
	s_addc_u32 s11, s11, 0
	global_load_ushort v26, v6, s[10:11]
	global_load_ushort v27, v6, s[10:11] offset:2048
	s_add_u32 s10, s10, 0x1000
	s_addc_u32 s11, s11, 0
	global_load_ushort v28, v6, s[10:11]
	global_load_ushort v29, v6, s[10:11] offset:2048
	s_add_u32 s10, s10, 0x1000
	s_addc_u32 s11, s11, 0
	global_load_ushort v30, v6, s[10:11]
	global_load_ushort v31, v6, s[10:11] offset:2048
	s_add_u32 s10, s10, 0x1000
	s_addc_u32 s11, s11, 0
	global_load_ushort v32, v6, s[10:11]
	global_load_ushort v33, v6, s[10:11] offset:2048
	s_add_u32 s10, s10, 0x1000
	s_addc_u32 s11, s11, 0
	global_load_ushort v34, v6, s[10:11]
	global_load_ushort v35, v6, s[10:11] offset:2048
	s_add_u32 s10, s10, 0x1000
	s_addc_u32 s11, s11, 0
	global_load_ushort v36, v6, s[10:11]
	global_load_ushort v37, v6, s[10:11] offset:2048
	s_add_u32 s10, s10, 0x1000
	s_addc_u32 s11, s11, 0
	global_load_ushort v38, v6, s[10:11]
	global_load_ushort v39, v6, s[10:11] offset:2048
	s_add_u32 s10, s10, 0x1000
	s_addc_u32 s11, s11, 0
	global_load_ushort v40, v6, s[10:11]
	global_load_ushort v41, v6, s[10:11] offset:2048
	s_add_u32 s10, s10, 0x1000
	s_addc_u32 s11, s11, 0
	global_load_ushort v42, v6, s[10:11]
	global_load_ushort v43, v6, s[10:11] offset:2048
	s_add_u32 s10, s10, 0x1000
	s_addc_u32 s11, s11, 0
	global_load_ushort v44, v6, s[10:11]
	global_load_ushort v45, v6, s[10:11] offset:2048
	s_add_u32 s10, s10, 0x1000
	s_addc_u32 s11, s11, 0
	global_load_ushort v46, v6, s[10:11]
	global_load_ushort v47, v6, s[10:11] offset:2048
	s_add_u32 s10, s10, 0x1000
	s_addc_u32 s11, s11, 0
	s_waitcnt vmcnt(0)
	v_lshlrev_b32_e32 v8, 16, v16
	v_add_f32_e32 v7, v7, v8
	v_lshlrev_b32_e32 v8, 16, v17
	v_add_f32_e32 v7, v7, v8
	v_lshlrev_b32_e32 v8, 16, v18
	v_add_f32_e32 v7, v7, v8
	v_lshlrev_b32_e32 v8, 16, v19
	v_add_f32_e32 v7, v7, v8
	v_lshlrev_b32_e32 v8, 16, v20
	v_add_f32_e32 v7, v7, v8
	v_lshlrev_b32_e32 v8, 16, v21
	v_add_f32_e32 v7, v7, v8
	v_lshlrev_b32_e32 v8, 16, v22
	v_add_f32_e32 v7, v7, v8
	v_lshlrev_b32_e32 v8, 16, v23
	v_add_f32_e32 v7, v7, v8
	v_lshlrev_b32_e32 v8, 16, v24
	v_add_f32_e32 v7, v7, v8
	v_lshlrev_b32_e32 v8, 16, v25
	v_add_f32_e32 v7, v7, v8
	v_lshlrev_b32_e32 v8, 16, v26
	v_add_f32_e32 v7, v7, v8
	v_lshlrev_b32_e32 v8, 16, v27
	v_add_f32_e32 v7, v7, v8
	v_lshlrev_b32_e32 v8, 16, v28
	v_add_f32_e32 v7, v7, v8
	v_lshlrev_b32_e32 v8, 16, v29
	v_add_f32_e32 v7, v7, v8
	v_lshlrev_b32_e32 v8, 16, v30
	v_add_f32_e32 v7, v7, v8
	v_lshlrev_b32_e32 v8, 16, v31
	v_add_f32_e32 v7, v7, v8
	v_lshlrev_b32_e32 v8, 16, v32
	v_add_f32_e32 v7, v7, v8
	v_lshlrev_b32_e32 v8, 16, v33
	v_add_f32_e32 v7, v7, v8
	v_lshlrev_b32_e32 v8, 16, v34
	v_add_f32_e32 v7, v7, v8
	v_lshlrev_b32_e32 v8, 16, v35
	v_add_f32_e32 v7, v7, v8
	v_lshlrev_b32_e32 v8, 16, v36
	v_add_f32_e32 v7, v7, v8
	v_lshlrev_b32_e32 v8, 16, v37
	v_add_f32_e32 v7, v7, v8
	v_lshlrev_b32_e32 v8, 16, v38
	v_add_f32_e32 v7, v7, v8
	v_lshlrev_b32_e32 v8, 16, v39
	v_add_f32_e32 v7, v7, v8
	v_lshlrev_b32_e32 v8, 16, v40
	v_add_f32_e32 v7, v7, v8
	v_lshlrev_b32_e32 v8, 16, v41
	v_add_f32_e32 v7, v7, v8
	v_lshlrev_b32_e32 v8, 16, v42
	v_add_f32_e32 v7, v7, v8
	v_lshlrev_b32_e32 v8, 16, v43
	v_add_f32_e32 v7, v7, v8
	v_lshlrev_b32_e32 v8, 16, v44
	v_add_f32_e32 v7, v7, v8
	v_lshlrev_b32_e32 v8, 16, v45
	v_add_f32_e32 v7, v7, v8
	v_lshlrev_b32_e32 v8, 16, v46
	v_add_f32_e32 v7, v7, v8
	v_lshlrev_b32_e32 v8, 16, v47
	v_add_f32_e32 v7, v7, v8
	s_add_i32 s12, s12, 1
	s_cmp_lt_u32 s12, 4
	s_cbranch_scc1 .Lmy_km_loop
	v_mov_b32_e32 v8, v7
	s_nop 1
	v_permlane32_swap_b32_e32 v7, v8
	s_nop 1
	v_add_f32_e32 v7, v7, v8
	v_mul_f32_e32 v7, 0x3b800000, v7
	v_bfe_u32 v8, v7, 16, 1
	s_movk_i32 s14, 0x7fff
	v_add3_u32 v7, v7, v8, s14
	v_lshrrev_b32_e32 v8, 7, v4
	v_lshl_add_u32 v8, v8, 6, v2
	v_and_b32_e32 v9, 0x7f, v4
	v_lshl_or_b32 v8, v8, 7, v9
	v_lshlrev_b32_e32 v8, 1, v8
	s_add_u32 s6, s8, 0x40000
	s_addc_u32 s7, s9, 0
	s_mov_b64 s[0:1], exec
	s_mov_b32 exec_hi, 0
	global_store_short_d16_hi v8, v7, s[6:7]
	s_mov_b64 exec, s[0:1]
	s_branch .LBB0_643
